# mixer-B PV: V fragments double-buffered (transposed reads issued two groups ahead), K/V global loads moved behind PV
# speedup vs baseline: 1.0012x; 1.0012x over previous
; #define SBAR() __builtin_amdgcn_sched_barrier(0)
; template <int OFF> __device__ __forceinline__ s16x4 tr_read(int vb) { s16x4 r; asm volatile("ds_read_b64_tr_b16 %0, %1 offset:%2" : "=&v"(r) : "v"(vb), "i"(OFF) : "memory"); return r; }
; #define SLOAD(i, k0) do { sr_[i].vs0 = *(const bf16x8*)(Vh + (size_t)((k0) + sr) * PW + sc); sr_[i].vs1 = *(const bf16x8*)(Vh + (size_t)((k0) + 32 + sr) * PW + sc); \
;     sr_[i].ks0 = *(const bf16x8*)(Kh + (size_t)((k0) + sr) * PW + sc); sr_[i].ks1 = *(const bf16x8*)(Kh + (size_t)((k0) + 32 + sr) * PW + sc); } while (0)
; template <int D0> __device__ __forceinline__ void pv_one(f32x16& od, int vb, bf16x8 pa0, bf16x8 pa1, bf16x8 pa2, bf16x8 pa3) {
;     s16x4 l0 = tr_read<v_rd_off(D0, 0, 0)>(vb), h0 = tr_read<v_rd_off(D0, 0, 1)>(vb), l1 = tr_read<v_rd_off(D0, 1, 0)>(vb), h1 = tr_read<v_rd_off(D0, 1, 1)>(vb);
;     s16x4 l2 = tr_read<v_rd_off(D0, 2, 0)>(vb), h2 = tr_read<v_rd_off(D0, 2, 1)>(vb), l3 = tr_read<v_rd_off(D0, 3, 0)>(vb), h3 = tr_read<v_rd_off(D0, 3, 1)>(vb);
;     asm volatile("s_waitcnt lgkmcnt(0)" : "+v"(l0), "+v"(h0), "+v"(l1), "+v"(h1), "+v"(l2), "+v"(h2), "+v"(l3), "+v"(h3) :: "memory");
;     od = __builtin_amdgcn_mfma_f32_32x32x16_bf16(pa0, PKV(l0, h0), od, 0, 0, 0);
;     od = __builtin_amdgcn_mfma_f32_32x32x16_bf16(pa1, PKV(l1, h1), od, 0, 0, 0);
;     od = __builtin_amdgcn_mfma_f32_32x32x16_bf16(pa2, PKV(l2, h2), od, 0, 0, 0);
;     od = __builtin_amdgcn_mfma_f32_32x32x16_bf16(pa3, PKV(l3, h3), od, 0, 0, 0);
; }
; __device__ __forceinline__ void pv_d0(f32x16* o, int vb, bf16x8 pa0, bf16x8 pa1, bf16x8 pa2, bf16x8 pa3) {
;     pv_one<0>(o[0], vb, pa0, pa1, pa2, pa3); pv_one<1>(o[1], vb, pa0, pa1, pa2, pa3); pv_one<2>(o[2], vb, pa0, pa1, pa2, pa3); pv_one<3>(o[3], vb, pa0, pa1, pa2, pa3);
; }
; __device__ __forceinline__ void unit(LAS unsigned char* lds, const bf16* __restrict__ PROJ, bf16* __restrict__ MIXED, const float* __restrict__ subln_g, float lam, int R0, int seq, int h, int qb) {
;     ...
;     for (int j = 1; j + 1 < NT; j += 2) {
;         SBAR(); qkt(pB0, pB1, K_lds + SHM_K, qr, r32, cb0);
;         finishSM(pA0, pA1, alA, l_reg, pa0, pa1, pa2, pa3); SBAR();
;         SLOAD(SO, (j + 2) * 64); SBAR();
;         pv_d0(o, vb0, pa0, pa1, pa2, pa3); partialSM(pB0, pB1, tbq + j * 64, rc0 + j * 64, cL, cR, m_reg, mnB, alB);
;         __syncthreads(); SWAIT(); SWRITE(0, SE);
.Lmb_pv_h1:
	ds_read_b64_tr_b16 v[128:129], v175 offset:512
	ds_read_b64_tr_b16 v[130:131], v175 offset:2560
	ds_read_b64_tr_b16 v[132:133], v175 offset:4608
	ds_read_b64_tr_b16 v[134:135], v175 offset:6656
	ds_read_b64_tr_b16 v[136:137], v175 offset:8704
	ds_read_b64_tr_b16 v[138:139], v175 offset:10752
	ds_read_b64_tr_b16 v[140:141], v175 offset:12800
	ds_read_b64_tr_b16 v[142:143], v175 offset:14848
	s_waitcnt lgkmcnt(8)
	v_mfma_f32_32x32x16_bf16 v[0:15], v[232:235], v[240:243], v[0:15]
	ds_read_b64_tr_b16 v[240:241], v175 offset:1024
	ds_read_b64_tr_b16 v[242:243], v175 offset:3072
	v_mfma_f32_32x32x16_bf16 v[0:15], v[236:239], v[244:247], v[0:15]
	ds_read_b64_tr_b16 v[244:245], v175 offset:5120
	ds_read_b64_tr_b16 v[246:247], v175 offset:7168
	v_max3_f32 v254, v80, v81, v82
	v_max3_f32 v255, v83, v84, v85
	v_max3_f32 v254, v254, v86, v87
	v_max3_f32 v255, v255, v88, v89
	v_max3_f32 v254, v254, v90, v91
	v_max3_f32 v255, v255, v92, v93
	v_mfma_f32_32x32x16_bf16 v[0:15], v[144:147], v[152:155], v[0:15]
	ds_read_b64_tr_b16 v[152:153], v175 offset:9216
	ds_read_b64_tr_b16 v[154:155], v175 offset:11264
	v_max3_f32 v254, v254, v94, v95
	v_max3_f32 v255, v255, v64, v65
	v_max3_f32 v254, v254, v66, v67
	v_max3_f32 v255, v255, v68, v69
	v_max3_f32 v254, v254, v70, v71
	v_max3_f32 v255, v255, v72, v73
	v_mfma_f32_32x32x16_bf16 v[0:15], v[148:151], v[156:159], v[0:15]
	ds_read_b64_tr_b16 v[156:157], v175 offset:13312
	ds_read_b64_tr_b16 v[158:159], v175 offset:15360
	v_max3_f32 v254, v254, v74, v75
	v_max3_f32 v255, v255, v76, v77
	v_max3_f32 v254, v254, v78, v79
	v_max_f32_e32 v254, v254, v255
	v_mov_b32_e32 v255, v254
	s_waitcnt lgkmcnt(8)
	v_mfma_f32_32x32x16_bf16 v[48:63], v[232:235], v[128:131], v[48:63]
	ds_read_b64_tr_b16 v[128:129], v175 offset:1536
	ds_read_b64_tr_b16 v[130:131], v175 offset:3584
	v_permlane32_swap_b32_e32 v254, v255
	v_max_f32_e32 v254, v254, v255
	v_add_f32_e32 v254, v249, v254
	v_sub_f32_e32 v255, v254, v250
	v_cmp_ge_f32_e32 vcc, s35, v255
	v_max_f32_e32 v255, v250, v254
	v_mfma_f32_32x32x16_bf16 v[48:63], v[236:239], v[132:135], v[48:63]
	ds_read_b64_tr_b16 v[132:133], v175 offset:5632
	ds_read_b64_tr_b16 v[134:135], v175 offset:7680
	v_sub_f32_e32 v248, v250, v255
	v_exp_f32_e32 v248, v248
	v_sub_f32_e32 v252, v255, v249
	v_sub_f32_e32 v254, v250, v249
	s_cmp_eq_u64 vcc, exec
	s_cselect_b64 s[4:5], -1, 0
	v_cndmask_b32_e64 v251, v248, 1.0, s[4:5]
	v_mfma_f32_32x32x16_bf16 v[48:63], v[144:147], v[136:139], v[48:63]
	ds_read_b64_tr_b16 v[136:137], v175 offset:9728
	ds_read_b64_tr_b16 v[138:139], v175 offset:11776
	v_cndmask_b32_e64 v250, v255, v250, s[4:5]
	v_cndmask_b32_e64 v252, v252, v254, s[4:5]
	v_sub_f32_e32 v80, v80, v252
	v_sub_f32_e32 v81, v81, v252
	v_sub_f32_e32 v82, v82, v252
	v_sub_f32_e32 v83, v83, v252
	v_mfma_f32_32x32x16_bf16 v[48:63], v[148:151], v[140:143], v[48:63]
	ds_read_b64_tr_b16 v[140:141], v175 offset:13824
	ds_read_b64_tr_b16 v[142:143], v175 offset:15872
	v_sub_f32_e32 v84, v84, v252
	v_sub_f32_e32 v85, v85, v252
	v_sub_f32_e32 v86, v86, v252
	v_sub_f32_e32 v87, v87, v252
	v_sub_f32_e32 v88, v88, v252
	v_sub_f32_e32 v89, v89, v252
	s_waitcnt lgkmcnt(8)
	v_mfma_f32_32x32x16_bf16 v[32:47], v[232:235], v[240:243], v[32:47]
	v_sub_f32_e32 v90, v90, v252
	v_sub_f32_e32 v91, v91, v252
	v_sub_f32_e32 v92, v92, v252
	v_sub_f32_e32 v93, v93, v252
	v_sub_f32_e32 v94, v94, v252
	v_sub_f32_e32 v95, v95, v252
	v_mfma_f32_32x32x16_bf16 v[32:47], v[236:239], v[244:247], v[32:47]
	v_exp_f32_e32 v80, v80
	v_sub_f32_e32 v64, v64, v252
	v_exp_f32_e32 v81, v81
	v_sub_f32_e32 v65, v65, v252
	v_mfma_f32_32x32x16_bf16 v[32:47], v[144:147], v[152:155], v[32:47]
	v_exp_f32_e32 v82, v82
	v_sub_f32_e32 v66, v66, v252
	v_exp_f32_e32 v83, v83
	v_sub_f32_e32 v67, v67, v252
	v_mfma_f32_32x32x16_bf16 v[32:47], v[148:151], v[156:159], v[32:47]
	v_exp_f32_e32 v84, v84
	v_sub_f32_e32 v68, v68, v252
	v_exp_f32_e32 v85, v85
	v_sub_f32_e32 v69, v69, v252
	s_waitcnt lgkmcnt(0)
	v_mfma_f32_32x32x16_bf16 v[16:31], v[232:235], v[128:131], v[16:31]
	v_exp_f32_e32 v86, v86
	v_sub_f32_e32 v70, v70, v252
	v_exp_f32_e32 v87, v87
	v_sub_f32_e32 v71, v71, v252
	v_mfma_f32_32x32x16_bf16 v[16:31], v[236:239], v[132:135], v[16:31]
	v_exp_f32_e32 v88, v88
	v_sub_f32_e32 v72, v72, v252
	v_exp_f32_e32 v89, v89
	v_sub_f32_e32 v73, v73, v252
	v_mfma_f32_32x32x16_bf16 v[16:31], v[144:147], v[136:139], v[16:31]
	v_exp_f32_e32 v90, v90
	v_sub_f32_e32 v74, v74, v252
	v_exp_f32_e32 v91, v91
	v_sub_f32_e32 v75, v75, v252
	v_mfma_f32_32x32x16_bf16 v[16:31], v[148:151], v[140:143], v[16:31]
	v_exp_f32_e32 v92, v92
	v_sub_f32_e32 v76, v76, v252
	v_exp_f32_e32 v93, v93
	v_sub_f32_e32 v77, v77, v252
	v_exp_f32_e32 v94, v94
	v_sub_f32_e32 v78, v78, v252
	v_exp_f32_e32 v95, v95
	v_sub_f32_e32 v79, v79, v252
	s_mov_b32 s4, 0xffee0000
	s_mov_b32 s5, -1
	v_lshl_add_u64 v[128:129], v[182:183], 0, s[4:5]
	global_load_dwordx4 v[128:131], v[128:129], off
	s_mov_b32 s4, 0xfff40000
	v_lshl_add_u64 v[140:141], v[182:183], 0, s[4:5]
	global_load_dwordx4 v[140:143], v[140:141], off
	s_and_b64 vcc, exec, s[26:27]
	s_cbranch_vccnz .Lmb_skipk1
	s_mov_b32 s4, 0xfffa0000
	v_lshl_add_u64 v[132:133], v[182:183], 0, s[4:5]
	global_load_dwordx4 v[132:135], v[132:133], off offset:-2048
	global_load_dwordx4 v[136:139], v[182:183], off offset:-2048
.Lmb_skipk1:
	s_barrier
	s_waitcnt vmcnt(4)
	s_and_b64 vcc, exec, s[26:27]
	s_cbranch_vccz .Lmb_w1
	s_waitcnt vmcnt(2)

; #define LAS __attribute__((address_space(3)))
; #define SBAR() __builtin_amdgcn_sched_barrier(0)
; #define SLOAD(i, k0) do { sr_[i].vs0 = *(const bf16x8*)(Vh + (size_t)((k0) + sr) * PW + sc); sr_[i].vs1 = *(const bf16x8*)(Vh + (size_t)((k0) + 32 + sr) * PW + sc); \
;     sr_[i].ks0 = *(const bf16x8*)(Kh + (size_t)((k0) + sr) * PW + sc); sr_[i].ks1 = *(const bf16x8*)(Kh + (size_t)((k0) + 32 + sr) * PW + sc); } while (0)
; __device__ __forceinline__ void qkt(f32x16& p0, f32x16& p1, const LAS unsigned char* Ks, const bf16x8* qr, int r32, int cb0) {
; #pragma unroll
;     for (int i = 0; i < 16; ++i) { p0[i] = 0.f; p1[i] = 0.f; }
; #pragma unroll
;     for (int d0 = 0; d0 < 4; ++d0) { const int cb = cb0 + d0 * 32;
;         const bf16x8 b0 = *(const LAS bf16x8*)(Ks + KSWZ(r32, cb));
;         const bf16x8 b1 = *(const LAS bf16x8*)(Ks + KSWZ(32 + r32, cb));
;         p0 = __builtin_amdgcn_mfma_f32_32x32x16_bf16(b0, qr[d0], p0, 0, 0, 0);
;         p1 = __builtin_amdgcn_mfma_f32_32x32x16_bf16(b1, qr[d0], p1, 0, 0, 0); }
; __device__ __forceinline__ void unit(LAS unsigned char* lds, const bf16* __restrict__ PROJ, bf16* __restrict__ MIXED, const float* __restrict__ subln_g, float lam, int R0, int seq, int h, int qb) {
;     ...
;         SBAR(); qkt(pA0, pA1, K_lds, qr, r32, cb0);
;         finishSM(pB0, pB1, alB, l_reg, pa0, pa1, pa2, pa3); SBAR();
;         if (j + 3 < NT) SLOAD(SE, (j + 3) * 64); SBAR();
;         pv_d0(o, vb0 + SHM_V, pa0, pa1, pa2, pa3); partialSM(pA0, pA1, tbq + (j + 1) * 64, rc0 + (j + 1) * 64, cL, cR, m_reg, mnA, alA);
.Lmb_qkn_h2:
	s_waitcnt lgkmcnt(3)
	v_mfma_f32_32x32x16_bf16 v[232:247], v[120:123], v[100:103], v[232:247]
	v_permlane32_swap_b32_e32 v80, v82
	v_permlane32_swap_b32_e32 v81, v83
	v_permlane32_swap_b32_e32 v84, v86
	v_permlane32_swap_b32_e32 v85, v87
	s_waitcnt lgkmcnt(2)
	v_mfma_f32_32x32x16_bf16 v[144:159], v[124:127], v[100:103], v[144:159]
	v_permlane32_swap_b32_e32 v64, v66
	v_permlane32_swap_b32_e32 v65, v67
	v_permlane32_swap_b32_e32 v68, v70
	v_permlane32_swap_b32_e32 v69, v71
	s_waitcnt lgkmcnt(1)
	v_mfma_f32_32x32x16_bf16 v[232:247], v[112:115], v[96:99], v[232:247]
	s_waitcnt lgkmcnt(0)
	v_mfma_f32_32x32x16_bf16 v[144:159], v[116:119], v[96:99], v[144:159]
.Lmb_qkj_h2:
	s_cmp_eq_u32 s28, 1
	s_cbranch_scc0 .Lmb_pv_h2
	ds_read2_b32 v[88:89], v223 offset0:64 offset1:65
	ds_read2_b32 v[90:91], v223 offset0:66 offset1:67
	ds_read2_b32 v[92:93], v223 offset0:72 offset1:73
	ds_read2_b32 v[94:95], v223 offset0:74 offset1:75
	ds_read2_b32 v[72:73], v223 offset0:80 offset1:81
	ds_read2_b32 v[74:75], v223 offset0:82 offset1:83
	ds_read2_b32 v[76:77], v223 offset0:88 offset1:89
	ds_read2_b32 v[78:79], v223 offset0:90 offset1:91
	s_waitcnt lgkmcnt(0)
	v_pk_add_f32 v[232:233], v[232:233], v[88:89]
	v_pk_add_f32 v[234:235], v[234:235], v[90:91]
	v_pk_add_f32 v[236:237], v[236:237], v[92:93]
	v_pk_add_f32 v[238:239], v[238:239], v[94:95]
	v_pk_add_f32 v[240:241], v[240:241], v[72:73]
	v_pk_add_f32 v[242:243], v[242:243], v[74:75]
	v_pk_add_f32 v[244:245], v[244:245], v[76:77]
	v_pk_add_f32 v[246:247], v[246:247], v[78:79]
	ds_read2_b32 v[88:89], v223 offset0:96 offset1:97
	ds_read2_b32 v[90:91], v223 offset0:98 offset1:99
	ds_read2_b32 v[92:93], v223 offset0:104 offset1:105
	ds_read2_b32 v[94:95], v223 offset0:106 offset1:107
	ds_read2_b32 v[72:73], v223 offset0:112 offset1:113
	ds_read2_b32 v[74:75], v223 offset0:114 offset1:115
	ds_read2_b32 v[76:77], v223 offset0:120 offset1:121
	ds_read2_b32 v[78:79], v223 offset0:122 offset1:123
	s_waitcnt lgkmcnt(0)
	v_pk_add_f32 v[144:145], v[144:145], v[88:89]
	v_pk_add_f32 v[146:147], v[146:147], v[90:91]
	v_pk_add_f32 v[148:149], v[148:149], v[92:93]
	v_pk_add_f32 v[150:151], v[150:151], v[94:95]
	v_pk_add_f32 v[152:153], v[152:153], v[72:73]
	v_pk_add_f32 v[154:155], v[154:155], v[74:75]
	v_pk_add_f32 v[156:157], v[156:157], v[76:77]
	v_pk_add_f32 v[158:159], v[158:159], v[78:79]
	ds_read_b64_tr_b16 v[88:89], v186 offset:0
	ds_read_b64_tr_b16 v[90:91], v186 offset:2048
	ds_read_b64_tr_b16 v[92:93], v186 offset:4096
	ds_read_b64_tr_b16 v[94:95], v186 offset:6144
	ds_read_b64_tr_b16 v[72:73], v186 offset:8192
	ds_read_b64_tr_b16 v[74:75], v186 offset:10240
	ds_read_b64_tr_b16 v[76:77], v186 offset:12288
	ds_read_b64_tr_b16 v[78:79], v186 offset:14336
; #define SBAR() __builtin_amdgcn_sched_barrier(0)
; template <int OFF> __device__ __forceinline__ s16x4 tr_read(int vb) { s16x4 r; asm volatile("ds_read_b64_tr_b16 %0, %1 offset:%2" : "=&v"(r) : "v"(vb), "i"(OFF) : "memory"); return r; }
; #define SLOAD(i, k0) do { sr_[i].vs0 = *(const bf16x8*)(Vh + (size_t)((k0) + sr) * PW + sc); sr_[i].vs1 = *(const bf16x8*)(Vh + (size_t)((k0) + 32 + sr) * PW + sc); \
;     sr_[i].ks0 = *(const bf16x8*)(Kh + (size_t)((k0) + sr) * PW + sc); sr_[i].ks1 = *(const bf16x8*)(Kh + (size_t)((k0) + 32 + sr) * PW + sc); } while (0)
; template <int D0> __device__ __forceinline__ void pv_one(f32x16& od, int vb, bf16x8 pa0, bf16x8 pa1, bf16x8 pa2, bf16x8 pa3) {
;     s16x4 l0 = tr_read<v_rd_off(D0, 0, 0)>(vb), h0 = tr_read<v_rd_off(D0, 0, 1)>(vb), l1 = tr_read<v_rd_off(D0, 1, 0)>(vb), h1 = tr_read<v_rd_off(D0, 1, 1)>(vb);
;     s16x4 l2 = tr_read<v_rd_off(D0, 2, 0)>(vb), h2 = tr_read<v_rd_off(D0, 2, 1)>(vb), l3 = tr_read<v_rd_off(D0, 3, 0)>(vb), h3 = tr_read<v_rd_off(D0, 3, 1)>(vb);
;     asm volatile("s_waitcnt lgkmcnt(0)" : "+v"(l0), "+v"(h0), "+v"(l1), "+v"(h1), "+v"(l2), "+v"(h2), "+v"(l3), "+v"(h3) :: "memory");
;     od = __builtin_amdgcn_mfma_f32_32x32x16_bf16(pa0, PKV(l0, h0), od, 0, 0, 0);
;     od = __builtin_amdgcn_mfma_f32_32x32x16_bf16(pa1, PKV(l1, h1), od, 0, 0, 0);
;     od = __builtin_amdgcn_mfma_f32_32x32x16_bf16(pa2, PKV(l2, h2), od, 0, 0, 0);
;     od = __builtin_amdgcn_mfma_f32_32x32x16_bf16(pa3, PKV(l3, h3), od, 0, 0, 0);
; }
; __device__ __forceinline__ void pv_d0(f32x16* o, int vb, bf16x8 pa0, bf16x8 pa1, bf16x8 pa2, bf16x8 pa3) {
;     pv_one<0>(o[0], vb, pa0, pa1, pa2, pa3); pv_one<1>(o[1], vb, pa0, pa1, pa2, pa3); pv_one<2>(o[2], vb, pa0, pa1, pa2, pa3); pv_one<3>(o[3], vb, pa0, pa1, pa2, pa3);
; }
; __device__ __forceinline__ void unit(LAS unsigned char* lds, const bf16* __restrict__ PROJ, bf16* __restrict__ MIXED, const float* __restrict__ subln_g, float lam, int R0, int seq, int h, int qb) {
;     ...
;         SBAR(); qkt(pA0, pA1, K_lds, qr, r32, cb0);
;         finishSM(pB0, pB1, alB, l_reg, pa0, pa1, pa2, pa3); SBAR();
;         if (j + 3 < NT) SLOAD(SE, (j + 3) * 64); SBAR();
;         pv_d0(o, vb0 + SHM_V, pa0, pa1, pa2, pa3); partialSM(pA0, pA1, tbq + (j + 1) * 64, rc0 + (j + 1) * 64, cL, cR, m_reg, mnA, alA);
;         __syncthreads(); SWAIT(); SWRITE(1, SO);
.Lmb_pv_h2:
	ds_read_b64_tr_b16 v[112:113], v186 offset:512
	ds_read_b64_tr_b16 v[114:115], v186 offset:2560
	ds_read_b64_tr_b16 v[116:117], v186 offset:4608
	ds_read_b64_tr_b16 v[118:119], v186 offset:6656
	ds_read_b64_tr_b16 v[120:121], v186 offset:8704
	ds_read_b64_tr_b16 v[122:123], v186 offset:10752
	ds_read_b64_tr_b16 v[124:125], v186 offset:12800
	ds_read_b64_tr_b16 v[126:127], v186 offset:14848
	s_waitcnt lgkmcnt(8)
	v_mfma_f32_32x32x16_bf16 v[0:15], v[80:83], v[88:91], v[0:15]
	ds_read_b64_tr_b16 v[88:89], v186 offset:1024
	ds_read_b64_tr_b16 v[90:91], v186 offset:3072
	v_mfma_f32_32x32x16_bf16 v[0:15], v[84:87], v[92:95], v[0:15]
	ds_read_b64_tr_b16 v[92:93], v186 offset:5120
	ds_read_b64_tr_b16 v[94:95], v186 offset:7168
	v_max3_f32 v254, v232, v233, v234
	v_max3_f32 v255, v235, v236, v237
	v_max3_f32 v254, v254, v238, v239
	v_max3_f32 v255, v255, v240, v241
	v_max3_f32 v254, v254, v242, v243
	v_max3_f32 v255, v255, v244, v245
	v_mfma_f32_32x32x16_bf16 v[0:15], v[64:67], v[72:75], v[0:15]
	ds_read_b64_tr_b16 v[72:73], v186 offset:9216
	ds_read_b64_tr_b16 v[74:75], v186 offset:11264
	v_max3_f32 v254, v254, v246, v247
	v_max3_f32 v255, v255, v144, v145
	v_max3_f32 v254, v254, v146, v147
	v_max3_f32 v255, v255, v148, v149
	v_max3_f32 v254, v254, v150, v151
	v_max3_f32 v255, v255, v152, v153
	v_mfma_f32_32x32x16_bf16 v[0:15], v[68:71], v[76:79], v[0:15]
	ds_read_b64_tr_b16 v[76:77], v186 offset:13312
	ds_read_b64_tr_b16 v[78:79], v186 offset:15360
	v_max3_f32 v254, v254, v154, v155
	v_max3_f32 v255, v255, v156, v157
	v_max3_f32 v254, v254, v158, v159
	v_max_f32_e32 v254, v254, v255
	v_mov_b32_e32 v255, v254
	s_waitcnt lgkmcnt(8)
	v_mfma_f32_32x32x16_bf16 v[48:63], v[80:83], v[112:115], v[48:63]
	ds_read_b64_tr_b16 v[112:113], v186 offset:1536
	ds_read_b64_tr_b16 v[114:115], v186 offset:3584
	v_permlane32_swap_b32_e32 v254, v255
	v_max_f32_e32 v254, v254, v255
	v_add_f32_e32 v254, v249, v254
	v_sub_f32_e32 v255, v254, v250
	v_cmp_ge_f32_e32 vcc, s35, v255
	v_max_f32_e32 v255, v250, v254
	v_mfma_f32_32x32x16_bf16 v[48:63], v[84:87], v[116:119], v[48:63]
	ds_read_b64_tr_b16 v[116:117], v186 offset:5632
	ds_read_b64_tr_b16 v[118:119], v186 offset:7680
	v_sub_f32_e32 v248, v250, v255
	v_exp_f32_e32 v248, v248
	v_sub_f32_e32 v252, v255, v249
	v_sub_f32_e32 v254, v250, v249
	s_cmp_eq_u64 vcc, exec
	s_cselect_b64 s[4:5], -1, 0
	v_cndmask_b32_e64 v251, v248, 1.0, s[4:5]
	v_mfma_f32_32x32x16_bf16 v[48:63], v[64:67], v[120:123], v[48:63]
	ds_read_b64_tr_b16 v[120:121], v186 offset:9728
	ds_read_b64_tr_b16 v[122:123], v186 offset:11776
	v_cndmask_b32_e64 v250, v255, v250, s[4:5]
	v_cndmask_b32_e64 v252, v252, v254, s[4:5]
	v_sub_f32_e32 v232, v232, v252
	v_sub_f32_e32 v233, v233, v252
	v_sub_f32_e32 v234, v234, v252
	v_sub_f32_e32 v235, v235, v252
	v_mfma_f32_32x32x16_bf16 v[48:63], v[68:71], v[124:127], v[48:63]
	ds_read_b64_tr_b16 v[124:125], v186 offset:13824
	ds_read_b64_tr_b16 v[126:127], v186 offset:15872
	v_sub_f32_e32 v236, v236, v252
	v_sub_f32_e32 v237, v237, v252
	v_sub_f32_e32 v238, v238, v252
	v_sub_f32_e32 v239, v239, v252
	v_sub_f32_e32 v240, v240, v252
	v_sub_f32_e32 v241, v241, v252
	s_waitcnt lgkmcnt(8)
	v_mfma_f32_32x32x16_bf16 v[32:47], v[80:83], v[88:91], v[32:47]
	v_sub_f32_e32 v242, v242, v252
	v_sub_f32_e32 v243, v243, v252
	v_sub_f32_e32 v244, v244, v252
	v_sub_f32_e32 v245, v245, v252
	v_sub_f32_e32 v246, v246, v252
	v_sub_f32_e32 v247, v247, v252
	v_mfma_f32_32x32x16_bf16 v[32:47], v[84:87], v[92:95], v[32:47]
	v_exp_f32_e32 v232, v232
	v_sub_f32_e32 v144, v144, v252
	v_exp_f32_e32 v233, v233
	v_sub_f32_e32 v145, v145, v252
	v_mfma_f32_32x32x16_bf16 v[32:47], v[64:67], v[72:75], v[32:47]
	v_exp_f32_e32 v234, v234
	v_sub_f32_e32 v146, v146, v252
	v_exp_f32_e32 v235, v235
	v_sub_f32_e32 v147, v147, v252
	v_mfma_f32_32x32x16_bf16 v[32:47], v[68:71], v[76:79], v[32:47]
	v_exp_f32_e32 v236, v236
	v_sub_f32_e32 v148, v148, v252
	v_exp_f32_e32 v237, v237
	v_sub_f32_e32 v149, v149, v252
	s_waitcnt lgkmcnt(0)
	v_mfma_f32_32x32x16_bf16 v[16:31], v[80:83], v[112:115], v[16:31]
	v_exp_f32_e32 v238, v238
	v_sub_f32_e32 v150, v150, v252
	v_exp_f32_e32 v239, v239
	v_sub_f32_e32 v151, v151, v252
	v_mfma_f32_32x32x16_bf16 v[16:31], v[84:87], v[116:119], v[16:31]
	v_exp_f32_e32 v240, v240
	v_sub_f32_e32 v152, v152, v252
	v_exp_f32_e32 v241, v241
	v_sub_f32_e32 v153, v153, v252
	v_mfma_f32_32x32x16_bf16 v[16:31], v[64:67], v[120:123], v[16:31]
	v_exp_f32_e32 v242, v242
	v_sub_f32_e32 v154, v154, v252
	v_exp_f32_e32 v243, v243
	v_sub_f32_e32 v155, v155, v252
	v_mfma_f32_32x32x16_bf16 v[16:31], v[68:71], v[124:127], v[16:31]
	v_exp_f32_e32 v244, v244
	v_sub_f32_e32 v156, v156, v252
	v_exp_f32_e32 v245, v245
	v_sub_f32_e32 v157, v157, v252
	v_exp_f32_e32 v246, v246
	v_sub_f32_e32 v158, v158, v252
	v_exp_f32_e32 v247, v247
	v_sub_f32_e32 v159, v159, v252
	s_and_b64 vcc, exec, s[26:27]
	s_cbranch_vccnz .Lmb_skipld
	s_mov_b32 s4, 0xfffa0000
	s_mov_b32 s5, -1
	v_lshl_add_u64 v[120:121], v[182:183], 0, s[4:5]
	global_load_dwordx4 v[120:123], v[120:121], off
	global_load_dwordx4 v[124:127], v[182:183], off
	s_mov_b64 s[4:5], 0x60000
	v_lshl_add_u64 v[112:113], v[182:183], 0, s[4:5]
	global_load_dwordx4 v[112:115], v[112:113], off offset:-2048
	s_mov_b64 s[4:5], 0xc0000
	v_lshl_add_u64 v[116:117], v[182:183], 0, s[4:5]
	global_load_dwordx4 v[116:119], v[116:117], off offset:-2048
.Lmb_skipld:
	s_barrier
	s_waitcnt vmcnt(4)
	s_and_b64 vcc, exec, s[26:27]
	s_cbranch_vccz .Lmb_w2
	s_waitcnt vmcnt(0)

; template <int OFF> __device__ __forceinline__ s16x4 tr_read(int vb) { s16x4 r; asm volatile("ds_read_b64_tr_b16 %0, %1 offset:%2" : "=&v"(r) : "v"(vb), "i"(OFF) : "memory"); return r; }
; #define RESC(a) do { if (__any((a) < 1.f)) { if (hi == 0) al_l[r32] = (a); LDS_WAIT(); \
;     _Pragma("unroll") for (int r = 0; r < 16; ++r) { const float av = al_l[crow(r, hi)]; _Pragma("unroll") for (int d = 0; d < 4; ++d) o[d][r] *= av; } } } while (0)
; template <int D0> __device__ __forceinline__ void pv_one(f32x16& od, int vb, bf16x8 pa0, bf16x8 pa1, bf16x8 pa2, bf16x8 pa3) {
;     s16x4 l0 = tr_read<v_rd_off(D0, 0, 0)>(vb), h0 = tr_read<v_rd_off(D0, 0, 1)>(vb), l1 = tr_read<v_rd_off(D0, 1, 0)>(vb), h1 = tr_read<v_rd_off(D0, 1, 1)>(vb);
;     s16x4 l2 = tr_read<v_rd_off(D0, 2, 0)>(vb), h2 = tr_read<v_rd_off(D0, 2, 1)>(vb), l3 = tr_read<v_rd_off(D0, 3, 0)>(vb), h3 = tr_read<v_rd_off(D0, 3, 1)>(vb);
;     asm volatile("s_waitcnt lgkmcnt(0)" : "+v"(l0), "+v"(h0), "+v"(l1), "+v"(h1), "+v"(l2), "+v"(h2), "+v"(l3), "+v"(h3) :: "memory");
;     od = __builtin_amdgcn_mfma_f32_32x32x16_bf16(pa0, PKV(l0, h0), od, 0, 0, 0);
;     od = __builtin_amdgcn_mfma_f32_32x32x16_bf16(pa1, PKV(l1, h1), od, 0, 0, 0);
;     od = __builtin_amdgcn_mfma_f32_32x32x16_bf16(pa2, PKV(l2, h2), od, 0, 0, 0);
;     od = __builtin_amdgcn_mfma_f32_32x32x16_bf16(pa3, PKV(l3, h3), od, 0, 0, 0);
; }
; __device__ __forceinline__ void pv_d0(f32x16* o, int vb, bf16x8 pa0, bf16x8 pa1, bf16x8 pa2, bf16x8 pa3) {
;     pv_one<0>(o[0], vb, pa0, pa1, pa2, pa3); pv_one<1>(o[1], vb, pa0, pa1, pa2, pa3); pv_one<2>(o[2], vb, pa0, pa1, pa2, pa3); pv_one<3>(o[3], vb, pa0, pa1, pa2, pa3);
; }
; __device__ __forceinline__ void unit(LAS unsigned char* lds, const bf16* __restrict__ PROJ, bf16* __restrict__ MIXED, const float* __restrict__ subln_g, float lam, int R0, int seq, int h, int qb) {
;     ...
;     pv_d0(o, vb0, pa0, pa1, pa2, pa3); partialSM(pB0, pB1, tbq + (NT - 1) * 64, rc0 + (NT - 1) * 64, cL, cR, m_reg, mnB, alB);
;     __syncthreads(); RESC(alB);
.Lmb_pv_pe:
	ds_read_b64_tr_b16 v[128:129], v175 offset:512
	ds_read_b64_tr_b16 v[130:131], v175 offset:2560
	ds_read_b64_tr_b16 v[132:133], v175 offset:4608
	ds_read_b64_tr_b16 v[134:135], v175 offset:6656
	ds_read_b64_tr_b16 v[136:137], v175 offset:8704
	ds_read_b64_tr_b16 v[138:139], v175 offset:10752
	ds_read_b64_tr_b16 v[140:141], v175 offset:12800
	ds_read_b64_tr_b16 v[142:143], v175 offset:14848
	s_nop 5
	s_waitcnt lgkmcnt(8)
	v_mfma_f32_32x32x16_bf16 v[0:15], v[232:235], v[240:243], v[0:15]
	ds_read_b64_tr_b16 v[240:241], v175 offset:1024
	ds_read_b64_tr_b16 v[242:243], v175 offset:3072
	v_mfma_f32_32x32x16_bf16 v[0:15], v[236:239], v[244:247], v[0:15]
	ds_read_b64_tr_b16 v[244:245], v175 offset:5120
	ds_read_b64_tr_b16 v[246:247], v175 offset:7168
	v_max3_f32 v254, v80, v81, v82
	v_max3_f32 v255, v83, v84, v85
	v_max3_f32 v254, v254, v86, v87
	v_max3_f32 v255, v255, v88, v89
	v_max3_f32 v254, v254, v90, v91
	v_max3_f32 v255, v255, v92, v93
	v_mfma_f32_32x32x16_bf16 v[0:15], v[144:147], v[152:155], v[0:15]
	ds_read_b64_tr_b16 v[152:153], v175 offset:9216
	ds_read_b64_tr_b16 v[154:155], v175 offset:11264
	v_max3_f32 v254, v254, v94, v95
	v_max3_f32 v255, v255, v64, v65
	v_max3_f32 v254, v254, v66, v67
	v_max3_f32 v255, v255, v68, v69
	v_max3_f32 v254, v254, v70, v71
	v_max3_f32 v255, v255, v72, v73
	v_mfma_f32_32x32x16_bf16 v[0:15], v[148:151], v[156:159], v[0:15]
	ds_read_b64_tr_b16 v[156:157], v175 offset:13312
	ds_read_b64_tr_b16 v[158:159], v175 offset:15360
	v_max3_f32 v254, v254, v74, v75
	v_max3_f32 v255, v255, v76, v77
	v_max3_f32 v254, v254, v78, v79
	v_max_f32_e32 v254, v254, v255
	v_mov_b32_e32 v255, v254
	s_waitcnt lgkmcnt(8)
	v_mfma_f32_32x32x16_bf16 v[48:63], v[232:235], v[128:131], v[48:63]
	ds_read_b64_tr_b16 v[128:129], v175 offset:1536
	ds_read_b64_tr_b16 v[130:131], v175 offset:3584
	v_permlane32_swap_b32_e32 v254, v255
	v_max_f32_e32 v254, v254, v255
	v_add_f32_e32 v254, v249, v254
	v_sub_f32_e32 v255, v254, v250
	v_cmp_ge_f32_e32 vcc, s35, v255
	v_max_f32_e32 v255, v250, v254
	v_mfma_f32_32x32x16_bf16 v[48:63], v[236:239], v[132:135], v[48:63]
	ds_read_b64_tr_b16 v[132:133], v175 offset:5632
	ds_read_b64_tr_b16 v[134:135], v175 offset:7680
	v_sub_f32_e32 v248, v250, v255
	v_exp_f32_e32 v248, v248
	v_sub_f32_e32 v252, v255, v249
	v_sub_f32_e32 v254, v250, v249
	s_cmp_eq_u64 vcc, exec
	s_cselect_b64 s[4:5], -1, 0
	v_cndmask_b32_e64 v251, v248, 1.0, s[4:5]
	v_mfma_f32_32x32x16_bf16 v[48:63], v[144:147], v[136:139], v[48:63]
	ds_read_b64_tr_b16 v[136:137], v175 offset:9728
	ds_read_b64_tr_b16 v[138:139], v175 offset:11776
	v_cndmask_b32_e64 v250, v255, v250, s[4:5]
	v_cndmask_b32_e64 v252, v252, v254, s[4:5]
	v_sub_f32_e32 v80, v80, v252
	v_sub_f32_e32 v81, v81, v252
	v_sub_f32_e32 v82, v82, v252
	v_sub_f32_e32 v83, v83, v252
	v_mfma_f32_32x32x16_bf16 v[48:63], v[148:151], v[140:143], v[48:63]
	ds_read_b64_tr_b16 v[140:141], v175 offset:13824
	ds_read_b64_tr_b16 v[142:143], v175 offset:15872
	v_sub_f32_e32 v84, v84, v252
	v_sub_f32_e32 v85, v85, v252
	v_sub_f32_e32 v86, v86, v252
	v_sub_f32_e32 v87, v87, v252
	v_sub_f32_e32 v88, v88, v252
	v_sub_f32_e32 v89, v89, v252
	s_waitcnt lgkmcnt(8)
	v_mfma_f32_32x32x16_bf16 v[32:47], v[232:235], v[240:243], v[32:47]
	v_sub_f32_e32 v90, v90, v252
	v_sub_f32_e32 v91, v91, v252
	v_sub_f32_e32 v92, v92, v252
	v_sub_f32_e32 v93, v93, v252
	v_sub_f32_e32 v94, v94, v252
	v_sub_f32_e32 v95, v95, v252
	v_mfma_f32_32x32x16_bf16 v[32:47], v[236:239], v[244:247], v[32:47]
	v_exp_f32_e32 v80, v80
	v_sub_f32_e32 v64, v64, v252
	v_exp_f32_e32 v81, v81
	v_sub_f32_e32 v65, v65, v252
	v_mfma_f32_32x32x16_bf16 v[32:47], v[144:147], v[152:155], v[32:47]
	v_exp_f32_e32 v82, v82
	v_sub_f32_e32 v66, v66, v252
	v_exp_f32_e32 v83, v83
	v_sub_f32_e32 v67, v67, v252
	v_mfma_f32_32x32x16_bf16 v[32:47], v[148:151], v[156:159], v[32:47]
	v_exp_f32_e32 v84, v84
	v_sub_f32_e32 v68, v68, v252
	v_exp_f32_e32 v85, v85
	v_sub_f32_e32 v69, v69, v252
	s_waitcnt lgkmcnt(0)
	v_mfma_f32_32x32x16_bf16 v[16:31], v[232:235], v[128:131], v[16:31]
	v_exp_f32_e32 v86, v86
	v_sub_f32_e32 v70, v70, v252
	v_exp_f32_e32 v87, v87
	v_sub_f32_e32 v71, v71, v252
	v_mfma_f32_32x32x16_bf16 v[16:31], v[236:239], v[132:135], v[16:31]
	v_exp_f32_e32 v88, v88
	v_sub_f32_e32 v72, v72, v252
	v_exp_f32_e32 v89, v89
	v_sub_f32_e32 v73, v73, v252
	v_mfma_f32_32x32x16_bf16 v[16:31], v[144:147], v[136:139], v[16:31]
	v_exp_f32_e32 v90, v90
	v_sub_f32_e32 v74, v74, v252
	v_exp_f32_e32 v91, v91
	v_sub_f32_e32 v75, v75, v252
	v_mfma_f32_32x32x16_bf16 v[16:31], v[148:151], v[140:143], v[16:31]
	v_exp_f32_e32 v92, v92
	v_sub_f32_e32 v76, v76, v252
	v_exp_f32_e32 v93, v93
	v_sub_f32_e32 v77, v77, v252
	v_exp_f32_e32 v94, v94
	v_sub_f32_e32 v78, v78, v252
	v_exp_f32_e32 v95, v95
	v_sub_f32_e32 v79, v79, v252
	s_waitcnt lgkmcnt(0)
	s_barrier
	s_and_b64 vcc, exec, s[4:5]
	s_cbranch_vccnz .Lmb_nr_pe
	s_and_saveexec_b64 s[28:29], s[0:1]
	ds_write_b32 v215, v251 offset:128
	s_or_b64 exec, exec, s[28:29]
	s_waitcnt lgkmcnt(0)
	ds_read_b128 v[112:115], v179 offset:224
	ds_read_b128 v[116:119], v179 offset:192
	ds_read_b128 v[120:123], v179 offset:160
	ds_read_b128 v[124:127], v179 offset:128
	s_waitcnt lgkmcnt(0)
	s_nop 3
	v_pk_mul_f32 v[14:15], v[14:15], v[114:115]
	v_pk_mul_f32 v[12:13], v[12:13], v[112:113]
	v_pk_mul_f32 v[10:11], v[10:11], v[118:119]
	v_pk_mul_f32 v[8:9], v[8:9], v[116:117]
	v_pk_mul_f32 v[6:7], v[6:7], v[122:123]
	v_pk_mul_f32 v[4:5], v[4:5], v[120:121]
	v_pk_mul_f32 v[2:3], v[2:3], v[126:127]
	v_pk_mul_f32 v[0:1], v[0:1], v[124:125]
	v_pk_mul_f32 v[62:63], v[62:63], v[114:115]
	v_pk_mul_f32 v[60:61], v[60:61], v[112:113]
	v_pk_mul_f32 v[58:59], v[58:59], v[118:119]
	v_pk_mul_f32 v[56:57], v[56:57], v[116:117]
	v_pk_mul_f32 v[54:55], v[54:55], v[122:123]
	v_pk_mul_f32 v[52:53], v[52:53], v[120:121]
	v_pk_mul_f32 v[50:51], v[50:51], v[126:127]
	v_pk_mul_f32 v[48:49], v[48:49], v[124:125]
	v_pk_mul_f32 v[46:47], v[46:47], v[114:115]
	v_pk_mul_f32 v[44:45], v[44:45], v[112:113]
	v_pk_mul_f32 v[42:43], v[42:43], v[118:119]
	v_pk_mul_f32 v[40:41], v[40:41], v[116:117]
	v_pk_mul_f32 v[38:39], v[38:39], v[122:123]
	v_pk_mul_f32 v[36:37], v[36:37], v[120:121]
	v_pk_mul_f32 v[34:35], v[34:35], v[126:127]
	v_pk_mul_f32 v[32:33], v[32:33], v[124:125]
	v_pk_mul_f32 v[30:31], v[30:31], v[114:115]
	v_pk_mul_f32 v[28:29], v[28:29], v[112:113]
	v_pk_mul_f32 v[26:27], v[26:27], v[118:119]
	v_pk_mul_f32 v[24:25], v[24:25], v[116:117]
	v_pk_mul_f32 v[22:23], v[22:23], v[122:123]
	v_pk_mul_f32 v[20:21], v[20:21], v[120:121]
	v_pk_mul_f32 v[18:19], v[18:19], v[126:127]
	v_pk_mul_f32 v[16:17], v[16:17], v[124:125]
; #define LDS_WAIT() asm volatile("s_waitcnt lgkmcnt(0)" ::: "memory")
; #define SBAR() __builtin_amdgcn_sched_barrier(0)
; __device__ __forceinline__ int crow(int r, int hi) { return (r & 3) + 8 * (r >> 2) + 4 * hi; }
; __device__ __forceinline__ float half_add(float v) { auto rr = __builtin_amdgcn_permlane32_swap(__float_as_uint(v), __float_as_uint(v), false, false); return __uint_as_float(rr[0]) + __uint_as_float(rr[1]); }
; __device__ __forceinline__ void finishSM(f32x16& p0, f32x16& p1, float alpha, float& l_reg, bf16x8& pa0, bf16x8& pa1, bf16x8& pa2, bf16x8& pa3) {
; #pragma unroll
;     for (int r = 0; r < 16; ++r) p1[r] = __builtin_amdgcn_exp2f(p1[r]);
;     float ps = 0;
; #pragma unroll
;     for (int r = 0; r < 16; ++r) ps += p0[r];
; #pragma unroll
;     for (int r = 0; r < 16; ++r) ps += p1[r];
;     ps = half_add(ps);
;     l_reg = l_reg * alpha + ps;
;     PK4(p0, 0, pa0); PK4(p0, 8, pa1); PK4(p1, 0, pa2); PK4(p1, 8, pa3);
; }
; __device__ __forceinline__ void unit(LAS unsigned char* lds, const bf16* __restrict__ PROJ, bf16* __restrict__ MIXED, const float* __restrict__ subln_g, float lam, int R0, int seq, int h, int qb) {
;     ...
;     finishSM(pB0, pB1, alB, l_reg, pa0, pa1, pa2, pa3); SBAR();
;     pv_d0(o, vb0 + SHM_V, pa0, pa1, pa2, pa3);
;     ...
;     if (hi == 0) li_l[r32] = l_reg; LDS_WAIT();
;     float rli[16];
; #pragma unroll
;     for (int r = 0; r < 16; ++r) rli[r] = __builtin_amdgcn_rcpf(li_l[crow(r, hi)]);
.Lmb_nr_pe:
	v_exp_f32_e32 v64, v64
	v_exp_f32_e32 v65, v65
	v_exp_f32_e32 v66, v66
	v_exp_f32_e32 v67, v67
	v_exp_f32_e32 v68, v68
	v_exp_f32_e32 v69, v69
	v_exp_f32_e32 v70, v70
	v_exp_f32_e32 v71, v71
	v_exp_f32_e32 v72, v72
	v_exp_f32_e32 v73, v73
	v_exp_f32_e32 v74, v74
	v_exp_f32_e32 v75, v75
	v_exp_f32_e32 v76, v76
	v_exp_f32_e32 v77, v77
	v_exp_f32_e32 v78, v78
	v_exp_f32_e32 v79, v79
	v_add_f32_e32 v254, v80, v81
	v_add_f32_e32 v255, v82, v83
	v_add_f32_e32 v254, v254, v84
	v_add_f32_e32 v255, v255, v85
	v_add_f32_e32 v254, v254, v86
	v_add_f32_e32 v255, v255, v87
	v_add_f32_e32 v254, v254, v88
	v_add_f32_e32 v255, v255, v89
	v_add_f32_e32 v254, v254, v90
	v_add_f32_e32 v255, v255, v91
	v_add_f32_e32 v254, v254, v92
	v_add_f32_e32 v255, v255, v93
	v_add_f32_e32 v254, v254, v94
	v_add_f32_e32 v255, v255, v95
	v_add_f32_e32 v254, v254, v64
	v_add_f32_e32 v255, v255, v65
	v_add_f32_e32 v254, v254, v66
	v_add_f32_e32 v255, v255, v67
	v_add_f32_e32 v254, v254, v68
	v_add_f32_e32 v255, v255, v69
	v_add_f32_e32 v254, v254, v70
	v_add_f32_e32 v255, v255, v71
	v_add_f32_e32 v254, v254, v72
	v_add_f32_e32 v255, v255, v73
	v_add_f32_e32 v254, v254, v74
	v_add_f32_e32 v255, v255, v75
	v_add_f32_e32 v254, v254, v76
	v_add_f32_e32 v255, v255, v77
	v_add_f32_e32 v254, v254, v78
	v_add_f32_e32 v255, v255, v79
	v_add_f32_e32 v254, v254, v255
	v_mov_b32_e32 v255, v254
	v_cvt_pk_bf16_f32 v80, v80, v81
	v_cvt_pk_bf16_f32 v81, v82, v83
	v_cvt_pk_bf16_f32 v82, v84, v85
	v_cvt_pk_bf16_f32 v83, v86, v87
	v_cvt_pk_bf16_f32 v84, v88, v89
	v_cvt_pk_bf16_f32 v85, v90, v91
	v_cvt_pk_bf16_f32 v86, v92, v93
	v_cvt_pk_bf16_f32 v87, v94, v95
	v_permlane32_swap_b32_e32 v254, v255
	v_cvt_pk_bf16_f32 v64, v64, v65
	v_cvt_pk_bf16_f32 v65, v66, v67
	v_cvt_pk_bf16_f32 v66, v68, v69
	v_cvt_pk_bf16_f32 v67, v70, v71
	v_cvt_pk_bf16_f32 v68, v72, v73
	v_cvt_pk_bf16_f32 v69, v74, v75
	v_cvt_pk_bf16_f32 v70, v76, v77
	v_cvt_pk_bf16_f32 v71, v78, v79
	v_add_f32_e32 v254, v254, v255
	v_fma_f32 v216, v216, v251, v254
	v_permlane32_swap_b32_e32 v80, v82
	v_permlane32_swap_b32_e32 v81, v83
	v_permlane32_swap_b32_e32 v84, v86
	v_permlane32_swap_b32_e32 v85, v87
	v_permlane32_swap_b32_e32 v64, v66
	v_permlane32_swap_b32_e32 v65, v67
	v_permlane32_swap_b32_e32 v68, v70
	v_permlane32_swap_b32_e32 v69, v71
	ds_read_b64_tr_b16 v[88:89], v186 offset:0
	ds_read_b64_tr_b16 v[90:91], v186 offset:2048
	ds_read_b64_tr_b16 v[92:93], v186 offset:4096
	ds_read_b64_tr_b16 v[94:95], v186 offset:6144
	ds_read_b64_tr_b16 v[72:73], v186 offset:8192
	ds_read_b64_tr_b16 v[74:75], v186 offset:10240
	ds_read_b64_tr_b16 v[76:77], v186 offset:12288
	ds_read_b64_tr_b16 v[78:79], v186 offset:14336
	ds_read_b64_tr_b16 v[128:129], v186 offset:512
	ds_read_b64_tr_b16 v[130:131], v186 offset:2560
	ds_read_b64_tr_b16 v[132:133], v186 offset:4608
	ds_read_b64_tr_b16 v[134:135], v186 offset:6656
	ds_read_b64_tr_b16 v[136:137], v186 offset:8704
	ds_read_b64_tr_b16 v[138:139], v186 offset:10752
	ds_read_b64_tr_b16 v[140:141], v186 offset:12800
	ds_read_b64_tr_b16 v[142:143], v186 offset:14848
	s_waitcnt lgkmcnt(8)
	v_mfma_f32_32x32x16_bf16 v[0:15], v[80:83], v[88:91], v[0:15]
	ds_read_b64_tr_b16 v[88:89], v186 offset:1024
	ds_read_b64_tr_b16 v[90:91], v186 offset:3072
	v_mfma_f32_32x32x16_bf16 v[0:15], v[84:87], v[92:95], v[0:15]
	ds_read_b64_tr_b16 v[92:93], v186 offset:5120
	ds_read_b64_tr_b16 v[94:95], v186 offset:7168
	v_mfma_f32_32x32x16_bf16 v[0:15], v[64:67], v[72:75], v[0:15]
	ds_read_b64_tr_b16 v[72:73], v186 offset:9216
	ds_read_b64_tr_b16 v[74:75], v186 offset:11264
	v_mfma_f32_32x32x16_bf16 v[0:15], v[68:71], v[76:79], v[0:15]
	ds_read_b64_tr_b16 v[76:77], v186 offset:13312
	ds_read_b64_tr_b16 v[78:79], v186 offset:15360
	s_waitcnt lgkmcnt(8)
	v_mfma_f32_32x32x16_bf16 v[48:63], v[80:83], v[128:131], v[48:63]
	ds_read_b64_tr_b16 v[128:129], v186 offset:1536
	ds_read_b64_tr_b16 v[130:131], v186 offset:3584
	v_mfma_f32_32x32x16_bf16 v[48:63], v[84:87], v[132:135], v[48:63]
	ds_read_b64_tr_b16 v[132:133], v186 offset:5632
	ds_read_b64_tr_b16 v[134:135], v186 offset:7680
	v_mfma_f32_32x32x16_bf16 v[48:63], v[64:67], v[136:139], v[48:63]
	ds_read_b64_tr_b16 v[136:137], v186 offset:9728
	ds_read_b64_tr_b16 v[138:139], v186 offset:11776
	v_mfma_f32_32x32x16_bf16 v[48:63], v[68:71], v[140:143], v[48:63]
	ds_read_b64_tr_b16 v[140:141], v186 offset:13824
	ds_read_b64_tr_b16 v[142:143], v186 offset:15872
	s_waitcnt lgkmcnt(8)
	v_mfma_f32_32x32x16_bf16 v[32:47], v[80:83], v[88:91], v[32:47]
	v_mfma_f32_32x32x16_bf16 v[32:47], v[84:87], v[92:95], v[32:47]
	v_mfma_f32_32x32x16_bf16 v[32:47], v[64:67], v[72:75], v[32:47]
	v_mfma_f32_32x32x16_bf16 v[32:47], v[68:71], v[76:79], v[32:47]
	s_waitcnt lgkmcnt(0)
	v_mfma_f32_32x32x16_bf16 v[16:31], v[80:83], v[128:131], v[16:31]
	v_mfma_f32_32x32x16_bf16 v[16:31], v[84:87], v[132:135], v[16:31]
	v_mfma_f32_32x32x16_bf16 v[16:31], v[64:67], v[136:139], v[16:31]
	v_mfma_f32_32x32x16_bf16 v[16:31], v[68:71], v[140:143], v[16:31]
	s_and_saveexec_b64 s[4:5], s[0:1]
	ds_write_b32 v215, v216
	s_or_b64 exec, exec, s[4:5]
	s_waitcnt lgkmcnt(0)
	ds_read_b128 v[64:67], v179
	ds_read_b128 v[68:71], v179 offset:32
	s_lshl_b32 s4, s95, 14
	s_add_i32 s6, s4, 0
	s_cmp_eq_u32 s71, 0
	s_waitcnt lgkmcnt(1)
	v_rcp_f32_e32 v80, v64
	v_rcp_f32_e32 v79, v65
	v_rcp_f32_e32 v78, v66
	v_rcp_f32_e32 v102, v67
	s_waitcnt lgkmcnt(0)
	v_rcp_f32_e32 v107, v68
	ds_read_b128 v[64:67], v179 offset:64
	v_rcp_f32_e32 v106, v69
	v_rcp_f32_e32 v105, v70
	v_rcp_f32_e32 v104, v71
	ds_read_b128 v[68:71], v179 offset:96
	s_waitcnt lgkmcnt(1)
	v_rcp_f32_e32 v97, v64
	v_rcp_f32_e32 v96, v65
	v_rcp_f32_e32 v95, v66
	v_rcp_f32_e32 v94, v67
	s_waitcnt lgkmcnt(0)
	v_rcp_f32_e32 v93, v68
	v_rcp_f32_e32 v92, v69
	v_rcp_f32_e32 v91, v70
	v_rcp_f32_e32 v90, v71
	s_cselect_b64 s[4:5], -1, 0
	s_and_b64 vcc, exec, s[4:5]
	v_lshl_add_u32 v98, v190, 2, s6
	s_barrier
; #define LAS __attribute__((address_space(3)))
; __device__ __forceinline__ void unit(LAS unsigned char* lds, const bf16* __restrict__ PROJ, bf16* __restrict__ MIXED, const float* __restrict__ subln_g, float lam, int R0, int seq, int h, int qb) {
;     ...
;     LAS float* xch = (LAS float*)lds + g * 4096;
;     if (c == 1) {
; #pragma unroll
;         for (int d = 0; d < 4; ++d)
; #pragma unroll
;             for (int r = 0; r < 16; ++r) xch[(d * 16 + r) * 64 + lane] = o[d][r] * rli[r]; }
	s_cbranch_vccnz .LBB0_294
	v_mul_f32_e32 v64, v0, v80
	v_mul_f32_e32 v65, v1, v79
	ds_write2st64_b32 v98, v64, v65 offset1:1
	v_mul_f32_e32 v64, v2, v78
	v_mul_f32_e32 v65, v3, v102
	ds_write2st64_b32 v98, v64, v65 offset0:2 offset1:3
	v_mul_f32_e32 v64, v4, v107
	v_mul_f32_e32 v65, v5, v106
	ds_write2st64_b32 v98, v64, v65 offset0:4 offset1:5
	v_mul_f32_e32 v64, v6, v105
	v_mul_f32_e32 v65, v7, v104
	ds_write2st64_b32 v98, v64, v65 offset0:6 offset1:7
	v_mul_f32_e32 v64, v8, v97
	v_mul_f32_e32 v65, v9, v96
	ds_write2st64_b32 v98, v64, v65 offset0:8 offset1:9
	v_mul_f32_e32 v64, v10, v95
	v_mul_f32_e32 v65, v11, v94
	ds_write2st64_b32 v98, v64, v65 offset0:10 offset1:11
	v_mul_f32_e32 v64, v12, v93
	v_mul_f32_e32 v65, v13, v92
	ds_write2st64_b32 v98, v64, v65 offset0:12 offset1:13
	v_mul_f32_e32 v64, v14, v91
	v_mul_f32_e32 v65, v15, v90
	ds_write2st64_b32 v98, v64, v65 offset0:14 offset1:15
	v_mul_f32_e32 v64, v48, v80
	v_mul_f32_e32 v65, v49, v79
	ds_write2st64_b32 v98, v64, v65 offset0:16 offset1:17
	v_mul_f32_e32 v64, v50, v78
	v_mul_f32_e32 v65, v51, v102
	ds_write2st64_b32 v98, v64, v65 offset0:18 offset1:19
	v_mul_f32_e32 v64, v52, v107
	v_mul_f32_e32 v65, v53, v106
	ds_write2st64_b32 v98, v64, v65 offset0:20 offset1:21
	v_mul_f32_e32 v64, v54, v105
	v_mul_f32_e32 v65, v55, v104
	ds_write2st64_b32 v98, v64, v65 offset0:22 offset1:23
	v_mul_f32_e32 v64, v56, v97
	v_mul_f32_e32 v65, v57, v96
	ds_write2st64_b32 v98, v64, v65 offset0:24 offset1:25
	v_mul_f32_e32 v64, v58, v95
	v_mul_f32_e32 v65, v59, v94
	ds_write2st64_b32 v98, v64, v65 offset0:26 offset1:27
	v_mul_f32_e32 v64, v60, v93
	v_mul_f32_e32 v65, v61, v92
	ds_write2st64_b32 v98, v64, v65 offset0:28 offset1:29
	v_mul_f32_e32 v64, v62, v91
	v_mul_f32_e32 v65, v63, v90
	ds_write2st64_b32 v98, v64, v65 offset0:30 offset1:31
	v_mul_f32_e32 v64, v32, v80
	v_mul_f32_e32 v65, v33, v79
	ds_write2st64_b32 v98, v64, v65 offset0:32 offset1:33
	v_mul_f32_e32 v64, v34, v78
	v_mul_f32_e32 v65, v35, v102
	ds_write2st64_b32 v98, v64, v65 offset0:34 offset1:35
	v_mul_f32_e32 v64, v36, v107
	v_mul_f32_e32 v65, v37, v106
	ds_write2st64_b32 v98, v64, v65 offset0:36 offset1:37
	v_mul_f32_e32 v64, v38, v105
	v_mul_f32_e32 v65, v39, v104
	ds_write2st64_b32 v98, v64, v65 offset0:38 offset1:39
	v_mul_f32_e32 v64, v40, v97
	v_mul_f32_e32 v65, v41, v96
	ds_write2st64_b32 v98, v64, v65 offset0:40 offset1:41
	v_mul_f32_e32 v64, v42, v95
	v_mul_f32_e32 v65, v43, v94
	ds_write2st64_b32 v98, v64, v65 offset0:42 offset1:43
	v_mul_f32_e32 v64, v44, v93
	v_mul_f32_e32 v65, v45, v92
	ds_write2st64_b32 v98, v64, v65 offset0:44 offset1:45
	v_mul_f32_e32 v64, v46, v91
	v_mul_f32_e32 v65, v47, v90
	ds_write2st64_b32 v98, v64, v65 offset0:46 offset1:47
	v_mul_f32_e32 v64, v16, v80
	v_mul_f32_e32 v65, v17, v79
	ds_write2st64_b32 v98, v64, v65 offset0:48 offset1:49
	v_mul_f32_e32 v64, v18, v78
	v_mul_f32_e32 v65, v19, v102
	ds_write2st64_b32 v98, v64, v65 offset0:50 offset1:51
	v_mul_f32_e32 v64, v20, v107
	v_mul_f32_e32 v65, v21, v106
	ds_write2st64_b32 v98, v64, v65 offset0:52 offset1:53
	v_mul_f32_e32 v64, v22, v105
	v_mul_f32_e32 v65, v23, v104
	ds_write2st64_b32 v98, v64, v65 offset0:54 offset1:55
	v_mul_f32_e32 v64, v24, v97
	v_mul_f32_e32 v65, v25, v96
	ds_write2st64_b32 v98, v64, v65 offset0:56 offset1:57
	v_mul_f32_e32 v64, v26, v95
	v_mul_f32_e32 v65, v27, v94
	ds_write2st64_b32 v98, v64, v65 offset0:58 offset1:59
	v_mul_f32_e32 v64, v28, v93
	v_mul_f32_e32 v65, v29, v92
	ds_write2st64_b32 v98, v64, v65 offset0:60 offset1:61
	v_mul_f32_e32 v64, v30, v91
	v_mul_f32_e32 v65, v31, v90
	ds_write2st64_b32 v98, v64, v65 offset0:62 offset1:63
